# MLA attention: half-stage stagger waves 4-7 (2nd barrier per stage after QK h1), DMA issue moved behind it
# speedup vs baseline: 1.0186x; 1.0039x over previous
.LBB0_515:
	v_readlane_b32 s2, v249, 46
	v_readlane_b32 s3, v249, 47
	s_mov_b64 s[6:7], s[58:59]
	s_andn2_b64 vcc, exec, s[2:3]
	s_waitcnt lgkmcnt(0)
	s_cbranch_vccnz .LBB0_538
	s_add_u32 s42, s6, 0x7a00000
	s_addc_u32 s43, s7, 0
	s_add_u32 s44, s6, 0xaa00000
	s_addc_u32 s45, s7, 0
	s_add_u32 s51, s6, 0x10a00000
	s_addc_u32 s71, s7, 0
	s_add_u32 s2, s6, 0xca00000
	s_addc_u32 s3, s7, 0
	s_add_u32 s72, s6, 0xea00000
	s_addc_u32 s73, s7, 0
	s_mov_b32 s75, 0
	v_readlane_b32 s74, v248, 13
	v_readfirstlane_b32 s101, v193
	s_nop 3
	s_lshr_b32 s101, s101, 8
	s_branch .LBB0_518

.LBB0_520:
	v_readlane_b32 s13, v248, 13
	s_sub_i32 s4, s74, s13
	s_lshl_b32 s4, s4, 2
	v_readlane_b32 s6, v251, 2
	s_ashr_i32 s8, s74, 3
	s_add_i32 s4, s4, s23
	v_readlane_b32 s7, v251, 3
	s_and_b64 s[6:7], s[6:7], exec
	s_cselect_b32 s36, s4, s8
	s_ashr_i32 s6, s36, 4
	s_ashr_i32 s37, s36, 31
	s_ashr_i32 s7, s6, 31
	s_lshl_b64 s[8:9], s[36:37], 18
	s_add_u32 s14, s44, s8
	s_addc_u32 s15, s45, s9
	s_lshl_b64 s[10:11], s[6:7], 17
	s_add_u32 s18, s51, s10
	s_addc_u32 s19, s71, s11
	s_add_u32 s24, s2, s8
	s_addc_u32 s25, s3, s9
	s_ashr_i32 s38, s0, 7
	s_lshl_b32 s0, s38, 11
	s_lshl_b32 s12, s16, 11
	s_add_i32 s29, s0, 0
	s_and_b32 s0, s16, 1
	s_add_i32 s28, s12, 0
	s_lshl_b32 s12, s0, 10
	s_add_i32 s29, s29, s12
	s_lshl_b32 s12, s16, 10
	s_sub_i32 s37, s28, s12
	v_and_b32_e32 v0, 63, v4
	s_cmp_le_i32 s74, s13
	v_lshlrev_b32_e32 v102, 3, v0
	s_cbranch_scc0 .LBB0_522
	s_ashr_i32 s17, s16, 31
	s_lshl_b64 s[12:13], s[16:17], 15
	s_add_u32 s40, s14, s12
	s_addc_u32 s41, s15, s13
	s_ashr_i32 s39, s38, 31
	s_lshl_b64 s[12:13], s[38:39], 11
	s_lshl_b32 s30, s0, 6
	s_or_b32 s12, s12, s30
	v_or_b32_e32 v186, s12, v0
	s_lshl_b32 s12, s16, 4
	v_mov_b32_e32 v187, s13
	s_ashr_i32 s13, s12, 31
	s_lshl_b64 s[54:55], s[12:13], 6
	s_add_u32 s54, s24, s54
	v_lshlrev_b32_e32 v6, 4, v0
	v_mov_b32_e32 v7, v1
	s_addc_u32 s55, s25, s55
	s_add_i32 s13, s28, s75
	s_waitcnt vmcnt(0)
	v_lshl_add_u64 v[8:9], s[40:41], 0, v[6:7]
	s_mov_b32 m0, s13
	v_lshlrev_b64 v[2:3], 4, v[186:187]
	global_load_lds_dwordx4 v6, s[40:41]
	v_lshl_add_u64 v[14:15], v[8:9], 0, s[26:27]
	s_add_i32 m0, s13, 0x400
	s_add_i32 s13, s29, s75
	v_lshl_add_u64 v[10:11], s[18:19], 0, v[2:3]
	global_load_lds_dwordx4 v[14:15], off
	s_add_i32 m0, s13, 0x4000
	s_add_i32 s13, s37, s75
	global_load_lds_dwordx4 v[10:11], off
	s_add_i32 m0, s13, 0x6000
	v_lshl_add_u64 v[12:13], s[54:55], 0, v[6:7]
	global_load_lds_dwordx4 v6, s[54:55]
	s_add_i32 m0, s13, 0x8000
	s_add_i32 s13, s75, 0xa000
	s_cmp_lt_i32 s75, 0x14000
	v_lshl_add_u64 v[6:7], v[12:13], 0, s[48:49]
	s_cselect_b32 s13, s13, 0
	s_mov_b64 s[30:31], 0x800
	global_load_lds_dwordx4 v[6:7], off
	v_lshl_add_u64 v[6:7], v[8:9], 0, s[30:31]
	v_lshl_add_u64 v[10:11], v[10:11], 0, s[30:31]
	s_mov_b64 s[40:41], 0x2000
	s_add_i32 s30, s28, s13
	v_lshl_add_u64 v[14:15], v[12:13], 0, s[40:41]
	s_mov_b32 m0, s30
	s_mov_b64 s[40:41], 0xc00
	global_load_lds_dwordx4 v[6:7], off
	v_lshl_add_u64 v[6:7], v[8:9], 0, s[40:41]
	s_add_i32 m0, s30, 0x400
	s_add_i32 s30, s29, s13
	global_load_lds_dwordx4 v[6:7], off
	s_add_i32 m0, s30, 0x4000
	s_add_i32 s13, s37, s13
	global_load_lds_dwordx4 v[10:11], off
	s_add_i32 m0, s13, 0x6000
	s_mov_b64 s[40:41], 0x22000
	global_load_lds_dwordx4 v[14:15], off
	v_lshl_add_u64 v[6:7], v[12:13], 0, s[40:41]
	s_add_i32 m0, s13, 0x8000
	v_mov_b32_e32 v103, v1
	global_load_lds_dwordx4 v[6:7], off
	s_cmp_eq_u32 s101, 0
	s_cbranch_scc1 .Lmla_nox
	s_waitcnt vmcnt(5)
	s_barrier
.Lmla_nox:
	s_cbranch_execz .LBB0_523
	s_branch .LBB0_524
.LBB0_522:
.LBB0_523:
	s_ashr_i32 s39, s38, 31
	s_lshl_b64 s[12:13], s[38:39], 11
	s_lshl_b32 s0, s0, 6
	s_or_b32 s0, s12, s0
	v_mov_b32_e32 v187, s13
	v_or_b32_e32 v186, s0, v0
	s_ashr_i32 s17, s16, 31
	s_lshl_b32 s12, s16, 4
	v_mov_b32_e32 v103, v1
	v_lshlrev_b64 v[2:3], 4, v[186:187]
.LBB0_524:
	v_readlane_b32 s30, v251, 2
	v_readlane_b32 s31, v251, 3
	s_and_b64 s[38:39], s[30:31], exec
	v_readlane_b32 s0, v251, 25
	s_cselect_b32 s0, s0, s74
	s_and_b32 s36, s36, 15
	s_mul_i32 s30, s6, 0x600000
	s_mul_hi_i32 s13, s6, 0x600000
	s_add_u32 s30, s42, s30
	s_addc_u32 s13, s43, s13
	s_mul_i32 s31, s36, 0xc0
	s_add_u32 s38, s30, s31
	s_addc_u32 s39, s13, 0
	s_lshl_b32 s0, s0, 8
	s_and_b32 s0, s0, 0x700
	v_and_b32_e32 v10, 31, v4
	v_or_b32_e32 v5, s0, v10
	v_lshrrev_b32_e32 v104, 5, v0
	v_lshl_add_u32 v188, s16, 5, v5
	v_mov_b64_e32 v[6:7], s[38:39]
	v_mad_i64_i32 v[6:7], s[38:39], v188, s47, v[6:7]
	v_lshlrev_b32_e32 v8, 4, v104
	v_mov_b32_e32 v9, v1
	s_lshl_b64 s[16:17], s[16:17], 11
	v_lshl_add_u64 v[6:7], v[6:7], 0, v[8:9]
	v_lshlrev_b32_e32 v5, 4, v4
	v_or_b32_e32 v191, s17, v1
	v_or_b32_e32 v190, s16, v0
	s_cmp_gt_i32 s75, 0x9fff
	flat_load_dwordx4 v[106:109], v[6:7]
	flat_load_dwordx4 v[110:113], v[6:7] offset:32
	flat_load_dwordx4 v[114:117], v[6:7] offset:64
	flat_load_dwordx4 v[118:121], v[6:7] offset:96
	flat_load_dwordx4 v[122:125], v[6:7] offset:128
	flat_load_dwordx4 v[126:129], v[6:7] offset:160
	v_and_b32_e32 v219, 0xc0, v5
	v_lshlrev_b32_e32 v5, 1, v4
	v_lshlrev_b32_e32 v4, 3, v4
	s_cselect_b32 s0, s68, 0x14000
	v_lshl_add_u64 v[6:7], v[190:191], 4, s[14:15]
	s_mov_b64 s[14:15], 0x1000
	v_lshl_add_u64 v[2:3], s[18:19], 0, v[2:3]
	s_ashr_i32 s13, s12, 31
	v_and_b32_e32 v227, 32, v5
	v_and_b32_e32 v228, 24, v4
	v_lshl_add_u64 v[4:5], v[102:103], 1, s[24:25]
	s_add_i32 s0, s0, s75
	v_lshl_add_u64 v[8:9], v[6:7], 0, s[14:15]
	v_lshl_add_u64 v[2:3], v[2:3], 0, s[14:15]
	s_lshl_b64 s[14:15], s[12:13], 6
	s_waitcnt vmcnt(5)
	v_lshl_add_u64 v[4:5], v[4:5], 0, s[14:15]
	s_mov_b64 s[14:15], 0x4000
	s_add_i32 s13, s28, s0
	v_lshlrev_b32_e32 v229, 4, v10
	s_waitcnt lgkmcnt(0)
	s_barrier
	v_lshl_add_u64 v[10:11], v[4:5], 0, s[14:15]
	s_mov_b32 m0, s13
	s_mov_b64 s[14:15], 0x1400
	global_load_lds_dwordx4 v[8:9], off
	v_lshl_add_u64 v[6:7], v[6:7], 0, s[14:15]
	s_add_i32 m0, s13, 0x400
	s_add_i32 s13, s29, s0
	global_load_lds_dwordx4 v[6:7], off
	s_add_i32 m0, s13, 0x4000
	s_add_i32 s0, s37, s0
	global_load_lds_dwordx4 v[2:3], off
	s_add_i32 m0, s0, 0x6000
	s_mov_b64 s[14:15], 0x24000
	global_load_lds_dwordx4 v[10:11], off
	v_lshl_add_u64 v[2:3], v[4:5], 0, s[14:15]
	s_add_i32 m0, s0, 0x8000
	v_lshlrev_b32_e32 v0, 11, v104
	global_load_lds_dwordx4 v[2:3], off
	s_add_i32 s0, s75, 0
	v_add3_u32 v82, s0, v0, v229
	ds_read_b128 v[50:53], v82
	ds_read_b128 v[18:21], v82 offset:512
	ds_read_b128 v[54:57], v82 offset:4096
	ds_read_b128 v[22:25], v82 offset:4608
	ds_read_b128 v[58:61], v82 offset:8192
	ds_read_b128 v[26:29], v82 offset:8704
	ds_read_b128 v[62:65], v82 offset:12288
	ds_read_b128 v[30:33], v82 offset:12800
	ds_read_b128 v[66:69], v82 offset:16384
	ds_read_b128 v[70:73], v82 offset:16896
	ds_read_b128 v[74:77], v82 offset:20480
	ds_read_b128 v[78:81], v82 offset:20992
	v_lshlrev_b32_e32 v218, 8, v104
	v_add_u32_e32 v2, s0, v218
	v_add3_u32 v83, v2, v219, v227
	v_readlane_b32 s76, v249, 60
	v_readlane_b32 s77, v249, 61
	v_readlane_b32 s78, v249, 62
	v_readlane_b32 s79, v249, 63
	v_readlane_b32 s80, v248, 0
	v_readlane_b32 s81, v248, 1
	v_readlane_b32 s82, v248, 2
	v_readlane_b32 s83, v248, 3
	v_readlane_b32 s84, v248, 4
	v_readlane_b32 s85, v248, 5
	v_readlane_b32 s86, v248, 6
	v_readlane_b32 s87, v248, 7
	v_readlane_b32 s88, v248, 8
	v_readlane_b32 s89, v248, 9
	v_readlane_b32 s90, v248, 10
	v_readlane_b32 s91, v248, 11
	v_mov_b64_e32 v[34:35], s[76:77]
	v_mov_b64_e32 v[36:37], s[78:79]
	v_mov_b64_e32 v[38:39], s[80:81]
	v_mov_b64_e32 v[40:41], s[82:83]
	v_mov_b64_e32 v[42:43], s[84:85]
	v_mov_b64_e32 v[44:45], s[86:87]
	v_mov_b64_e32 v[46:47], s[88:89]
	v_mov_b64_e32 v[48:49], s[90:91]
	s_waitcnt vmcnt(0) lgkmcnt(0)
	s_nop 0
	v_mfma_f32_32x32x16_bf16 v[2:17], v[18:21], v[106:109], v[34:49]
	v_mfma_f32_32x32x16_bf16 v[2:17], v[22:25], v[110:113], v[2:17]
	v_mfma_f32_32x32x16_bf16 v[2:17], v[26:29], v[114:117], v[2:17]
	v_mfma_f32_32x32x16_bf16 v[2:17], v[30:33], v[118:121], v[2:17]
	v_mfma_f32_32x32x16_bf16 v[2:17], v[70:73], v[122:125], v[2:17]
	v_mfma_f32_32x32x16_bf16 v[2:17], v[78:81], v[126:129], v[2:17]
	v_mfma_f32_32x32x16_bf16 v[18:33], v[50:53], v[106:109], v[34:49]
	v_add_u32_e32 v105, v83, v228
	ds_read_b128 v[70:73], v82 offset:1024
	ds_read_b128 v[130:133], v82 offset:1536
	ds_read_b128 v[78:81], v82 offset:5120
	ds_read_b128 v[134:137], v82 offset:5632
	ds_read_b128 v[138:141], v82 offset:9216
	ds_read_b128 v[142:145], v82 offset:9728
	v_mfma_f32_32x32x16_bf16 v[18:33], v[54:57], v[110:113], v[18:33]
	ds_read_b128 v[146:149], v82 offset:13312
	ds_read_b128 v[150:153], v82 offset:13824
	ds_read_b128 v[154:157], v82 offset:17408
	ds_read_b128 v[158:161], v82 offset:17920
	ds_read_b128 v[162:165], v82 offset:21504
	ds_read_b128 v[98:101], v82 offset:22016
	ds_read_b64_tr_b16 v[82:83], v105 offset:24576
	v_mfma_f32_32x32x16_bf16 v[18:33], v[58:61], v[114:117], v[18:33]
	ds_read_b64_tr_b16 v[84:85], v105 offset:25088
	ds_read_b64_tr_b16 v[86:87], v105 offset:25600
	ds_read_b64_tr_b16 v[88:89], v105 offset:26112
	ds_read_b64_tr_b16 v[90:91], v105 offset:26624
	ds_read_b64_tr_b16 v[92:93], v105 offset:27136
	ds_read_b64_tr_b16 v[94:95], v105 offset:27648
	ds_read_b64_tr_b16 v[96:97], v105 offset:28160
	v_mfma_f32_32x32x16_bf16 v[18:33], v[62:65], v[118:121], v[18:33]
	v_mfma_f32_32x32x16_bf16 v[18:33], v[66:69], v[122:125], v[18:33]
	v_mfma_f32_32x32x16_bf16 v[18:33], v[74:77], v[126:129], v[18:33]
	v_max_f32_e32 v34, v2, v2
	s_nop 10
	v_max_f32_e32 v35, v18, v18
	v_max_f32_e32 v34, v35, v34
	v_max3_f32 v34, v34, v19, v3
	v_max3_f32 v34, v34, v20, v4
	v_max3_f32 v34, v34, v21, v5
	v_max3_f32 v34, v34, v22, v6
	v_max3_f32 v34, v34, v23, v7
	v_max3_f32 v34, v34, v24, v8
	v_max3_f32 v34, v34, v25, v9
	v_max3_f32 v34, v34, v26, v10
	v_max3_f32 v34, v34, v27, v11
	v_max3_f32 v34, v34, v28, v12
	v_max3_f32 v34, v34, v29, v13
	v_max3_f32 v34, v34, v30, v14
	v_max3_f32 v34, v34, v31, v15
	v_max3_f32 v34, v34, v32, v16
	v_max3_f32 v34, v34, v33, v17
	v_mov_b32_e32 v35, v34
	s_nop 1
	v_permlane32_swap_b32_e32 v34, v35
	v_max_f32_e32 v35, v35, v35
	v_max_f32_e32 v34, v34, v34
	v_max_f32_e32 v40, v34, v35
	v_sub_f32_e32 v34, v2, v40
	v_sub_f32_e32 v2, v18, v40
	v_sub_f32_e32 v35, v3, v40
	v_sub_f32_e32 v36, v4, v40
	v_sub_f32_e32 v4, v19, v40
	v_exp_f32_e32 v2, v2
	v_exp_f32_e32 v3, v34
	v_sub_f32_e32 v37, v5, v40
	v_sub_f32_e32 v38, v6, v40
	v_sub_f32_e32 v6, v20, v40
	v_exp_f32_e32 v4, v4
	v_exp_f32_e32 v5, v35
	v_sub_f32_e32 v39, v7, v40
	v_sub_f32_e32 v41, v8, v40
	v_sub_f32_e32 v8, v21, v40
	v_exp_f32_e32 v6, v6
	v_exp_f32_e32 v7, v36
	v_sub_f32_e32 v42, v9, v40
	v_sub_f32_e32 v45, v12, v40
	v_sub_f32_e32 v12, v22, v40
	v_exp_f32_e32 v8, v8
	v_exp_f32_e32 v9, v37
	v_sub_f32_e32 v43, v10, v40
	v_sub_f32_e32 v44, v11, v40
	v_sub_f32_e32 v46, v13, v40
	v_sub_f32_e32 v47, v14, v40
	v_sub_f32_e32 v14, v23, v40
	v_pk_add_f32 v[10:11], v[2:3], 0 op_sel_hi:[1,0]
	v_exp_f32_e32 v12, v12
	v_exp_f32_e32 v13, v38
	v_sub_f32_e32 v48, v15, v40
	v_sub_f32_e32 v49, v16, v40
	v_sub_f32_e32 v16, v24, v40
	v_pk_add_f32 v[10:11], v[4:5], v[10:11]
	v_exp_f32_e32 v14, v14
	v_exp_f32_e32 v15, v39
	v_sub_f32_e32 v50, v17, v40
	v_sub_f32_e32 v18, v25, v40
	v_pk_add_f32 v[10:11], v[6:7], v[10:11]
	v_exp_f32_e32 v16, v16
	v_exp_f32_e32 v17, v41
	v_sub_f32_e32 v19, v26, v40
	v_pk_add_f32 v[10:11], v[8:9], v[10:11]
	v_exp_f32_e32 v22, v18
	v_exp_f32_e32 v23, v42
	v_sub_f32_e32 v20, v27, v40
	v_exp_f32_e32 v24, v19
	v_exp_f32_e32 v25, v43
	v_pk_add_f32 v[10:11], v[12:13], v[10:11]
	v_sub_f32_e32 v21, v28, v40
	v_exp_f32_e32 v26, v20
	v_exp_f32_e32 v27, v44
	v_pk_add_f32 v[10:11], v[14:15], v[10:11]
	v_sub_f32_e32 v51, v29, v40
	v_exp_f32_e32 v28, v21
	v_exp_f32_e32 v29, v45
	v_pk_add_f32 v[10:11], v[16:17], v[10:11]
	v_sub_f32_e32 v52, v30, v40
	v_sub_f32_e32 v53, v31, v40
	v_exp_f32_e32 v30, v51
	v_exp_f32_e32 v31, v46
	v_pk_add_f32 v[10:11], v[22:23], v[10:11]
	v_sub_f32_e32 v54, v32, v40
	v_sub_f32_e32 v55, v33, v40
	v_exp_f32_e32 v32, v52
	v_exp_f32_e32 v33, v47
	v_pk_add_f32 v[10:11], v[24:25], v[10:11]
	v_exp_f32_e32 v34, v53
	v_exp_f32_e32 v35, v48
	v_pk_add_f32 v[10:11], v[26:27], v[10:11]
	v_exp_f32_e32 v36, v54
	v_exp_f32_e32 v37, v49
	v_pk_add_f32 v[10:11], v[28:29], v[10:11]
	v_exp_f32_e32 v38, v55
	v_exp_f32_e32 v39, v50
	v_pk_add_f32 v[10:11], v[30:31], v[10:11]
	v_cvt_pk_bf16_f32 v18, v2, v4
	v_pk_add_f32 v[10:11], v[32:33], v[10:11]
	v_cvt_pk_bf16_f32 v170, v3, v5
	v_pk_add_f32 v[10:11], v[34:35], v[10:11]
	v_cvt_pk_bf16_f32 v168, v32, v34
	v_pk_add_f32 v[10:11], v[36:37], v[10:11]
	v_cvt_pk_bf16_f32 v19, v6, v8
	v_pk_add_f32 v[10:11], v[38:39], v[10:11]
	v_cvt_pk_bf16_f32 v20, v12, v14
	v_pk_add_f32 v[2:3], v[10:11], v[10:11] op_sel:[0,1] op_sel_hi:[1,0]
	v_cvt_pk_bf16_f32 v21, v16, v22
	v_mov_b32_e32 v3, v40
	v_pk_add_f32 v[214:215], v[2:3], 0 op_sel_hi:[1,0]
	v_cvt_pk_bf16_f32 v169, v36, v38
	v_xor_b32_e32 v34, 0x80000000, v215
	v_cvt_pk_bf16_f32 v176, v33, v35
	v_cvt_pk_bf16_f32 v177, v37, v39
	v_mov_b32_e32 v35, v34
	v_mov_b32_e32 v36, v34
	v_mov_b32_e32 v37, v34
	v_mov_b32_e32 v38, v34
	v_mov_b32_e32 v39, v34
	v_mov_b32_e32 v40, v34
	v_mov_b32_e32 v41, v34
	v_mov_b32_e32 v42, v34
	v_mov_b32_e32 v43, v34
	v_mov_b32_e32 v44, v34
	v_mov_b32_e32 v45, v34
	v_mov_b32_e32 v46, v34
	v_mov_b32_e32 v47, v34
	v_mov_b32_e32 v48, v34
	v_mov_b32_e32 v49, v34
	v_cvt_pk_bf16_f32 v166, v24, v26
	v_cvt_pk_bf16_f32 v167, v28, v30
	v_cvt_pk_bf16_f32 v171, v7, v9
	v_cvt_pk_bf16_f32 v172, v13, v15
	v_cvt_pk_bf16_f32 v173, v17, v23
	v_cvt_pk_bf16_f32 v174, v25, v27
	v_cvt_pk_bf16_f32 v175, v29, v31
	s_waitcnt lgkmcnt(14)
	v_mfma_f32_32x32x16_bf16 v[50:65], v[70:73], v[106:109], v[34:49]
	v_mfma_f32_32x32x16_bf16 v[50:65], v[78:81], v[110:113], v[50:65]
	v_mfma_f32_32x32x16_bf16 v[50:65], v[138:141], v[114:117], v[50:65]
	s_waitcnt lgkmcnt(13)
	v_mfma_f32_32x32x16_bf16 v[50:65], v[146:149], v[118:121], v[50:65]
	s_waitcnt lgkmcnt(11)
	v_mfma_f32_32x32x16_bf16 v[50:65], v[154:157], v[122:125], v[50:65]
	s_waitcnt lgkmcnt(9)
	v_mfma_f32_32x32x16_bf16 v[50:65], v[162:165], v[126:129], v[50:65]
	v_mfma_f32_32x32x16_bf16 v[66:81], v[130:133], v[106:109], v[34:49]
	v_mfma_f32_32x32x16_bf16 v[66:81], v[134:137], v[110:113], v[66:81]
	v_mfma_f32_32x32x16_bf16 v[66:81], v[142:145], v[114:117], v[66:81]
	v_mfma_f32_32x32x16_bf16 v[66:81], v[150:153], v[118:121], v[66:81]
	v_mfma_f32_32x32x16_bf16 v[66:81], v[158:161], v[122:125], v[66:81]
	s_waitcnt lgkmcnt(8)
	v_mfma_f32_32x32x16_bf16 v[66:81], v[98:101], v[126:129], v[66:81]
	s_barrier
	ds_read_b64_tr_b16 v[22:23], v105 offset:32768
	ds_read_b64_tr_b16 v[24:25], v105 offset:33280
	ds_read_b64_tr_b16 v[98:99], v105 offset:33792
	ds_read_b64_tr_b16 v[100:101], v105 offset:34304
	ds_read_b64_tr_b16 v[130:131], v105 offset:34816
	ds_read_b64_tr_b16 v[132:133], v105 offset:35328
	ds_read_b64_tr_b16 v[134:135], v105 offset:35840
	ds_read_b64_tr_b16 v[136:137], v105 offset:36352
	s_waitcnt lgkmcnt(14)
	v_mfma_f32_32x32x16_bf16 v[2:17], v[82:85], v[18:21], 0
	s_nop 1
	v_max_f32_e32 v82, v66, v66
	v_max_f32_e32 v83, v50, v50
	v_max_f32_e32 v82, v83, v82
	s_waitcnt lgkmcnt(12)
	v_mfma_f32_32x32x16_bf16 v[2:17], v[86:89], v[166:169], v[2:17]
	v_max3_f32 v82, v82, v51, v67
	v_max3_f32 v82, v82, v52, v68
	v_max3_f32 v82, v82, v53, v69
	s_waitcnt lgkmcnt(10)
	v_mfma_f32_32x32x16_bf16 v[2:17], v[90:93], v[170:173], v[2:17]
	v_max3_f32 v82, v82, v54, v70
	v_max3_f32 v82, v82, v55, v71
	v_max3_f32 v82, v82, v56, v72
	s_waitcnt lgkmcnt(8)
	v_mfma_f32_32x32x16_bf16 v[2:17], v[94:97], v[174:177], v[2:17]
	v_max3_f32 v82, v82, v57, v73
	v_max3_f32 v82, v82, v58, v74
	v_max3_f32 v82, v82, v59, v75
	s_waitcnt lgkmcnt(6)
	v_mfma_f32_32x32x16_bf16 v[18:33], v[22:25], v[18:21], 0
	v_max3_f32 v82, v82, v60, v76
	v_max3_f32 v82, v82, v61, v77
	v_max3_f32 v82, v82, v62, v78
	s_waitcnt lgkmcnt(4)
	v_mfma_f32_32x32x16_bf16 v[18:33], v[98:101], v[166:169], v[18:33]
	v_max3_f32 v82, v82, v63, v79
	v_max3_f32 v82, v82, v64, v80
	v_max3_f32 v82, v82, v65, v81
	s_waitcnt lgkmcnt(2)
	v_mfma_f32_32x32x16_bf16 v[18:33], v[130:133], v[170:173], v[18:33]
	v_mov_b32_e32 v83, v82
	s_nop 1
	v_permlane32_swap_b32_e32 v82, v83
	v_max_f32_e32 v83, v83, v83
	v_max_f32_e32 v82, v82, v82
	v_max_f32_e32 v82, v82, v83
	s_waitcnt lgkmcnt(0)
	v_mfma_f32_32x32x16_bf16 v[18:33], v[134:137], v[174:177], v[18:33]
	v_cmp_lt_f32_e32 vcc, s69, v82
	s_cbranch_vccz .LBB0_526
	v_max_f32_e32 v34, v82, v82
	v_max_f32_e32 v34, 0, v34
	v_exp_f32_e64 v36, -v34
	v_pk_add_f32 v[50:51], v[50:51], v[34:35] op_sel_hi:[1,0] neg_lo:[0,1] neg_hi:[0,1]
	v_pk_add_f32 v[66:67], v[66:67], v[34:35] op_sel_hi:[1,0] neg_lo:[0,1] neg_hi:[0,1]
	v_pk_add_f32 v[52:53], v[52:53], v[34:35] op_sel_hi:[1,0] neg_lo:[0,1] neg_hi:[0,1]
	v_pk_mul_f32 v[82:83], v[214:215], v[36:37]
	v_add_f32_e32 v215, v215, v34
	v_pk_add_f32 v[68:69], v[68:69], v[34:35] op_sel_hi:[1,0] neg_lo:[0,1] neg_hi:[0,1]
	v_pk_add_f32 v[54:55], v[54:55], v[34:35] op_sel_hi:[1,0] neg_lo:[0,1] neg_hi:[0,1]
	v_pk_add_f32 v[70:71], v[70:71], v[34:35] op_sel_hi:[1,0] neg_lo:[0,1] neg_hi:[0,1]
	v_pk_add_f32 v[56:57], v[56:57], v[34:35] op_sel_hi:[1,0] neg_lo:[0,1] neg_hi:[0,1]
	v_pk_add_f32 v[72:73], v[72:73], v[34:35] op_sel_hi:[1,0] neg_lo:[0,1] neg_hi:[0,1]
	v_pk_add_f32 v[58:59], v[58:59], v[34:35] op_sel_hi:[1,0] neg_lo:[0,1] neg_hi:[0,1]
	v_pk_add_f32 v[74:75], v[74:75], v[34:35] op_sel_hi:[1,0] neg_lo:[0,1] neg_hi:[0,1]
	v_pk_add_f32 v[60:61], v[60:61], v[34:35] op_sel_hi:[1,0] neg_lo:[0,1] neg_hi:[0,1]
	v_pk_add_f32 v[76:77], v[76:77], v[34:35] op_sel_hi:[1,0] neg_lo:[0,1] neg_hi:[0,1]
	v_pk_add_f32 v[62:63], v[62:63], v[34:35] op_sel_hi:[1,0] neg_lo:[0,1] neg_hi:[0,1]
	v_pk_add_f32 v[78:79], v[78:79], v[34:35] op_sel_hi:[1,0] neg_lo:[0,1] neg_hi:[0,1]
	v_pk_add_f32 v[64:65], v[64:65], v[34:35] op_sel_hi:[1,0] neg_lo:[0,1] neg_hi:[0,1]
	v_pk_add_f32 v[80:81], v[80:81], v[34:35] op_sel_hi:[1,0] neg_lo:[0,1] neg_hi:[0,1]
	v_xor_b32_e32 v34, 0x80000000, v215
	v_pk_mul_f32 v[16:17], v[16:17], v[36:37] op_sel_hi:[1,0]
	v_pk_mul_f32 v[14:15], v[14:15], v[36:37] op_sel_hi:[1,0]
	v_pk_mul_f32 v[12:13], v[12:13], v[36:37] op_sel_hi:[1,0]
	v_pk_mul_f32 v[10:11], v[10:11], v[36:37] op_sel_hi:[1,0]
	v_pk_mul_f32 v[8:9], v[8:9], v[36:37] op_sel_hi:[1,0]
	v_pk_mul_f32 v[6:7], v[6:7], v[36:37] op_sel_hi:[1,0]
	v_pk_mul_f32 v[4:5], v[4:5], v[36:37] op_sel_hi:[1,0]
	v_pk_mul_f32 v[2:3], v[2:3], v[36:37] op_sel_hi:[1,0]
	v_pk_mul_f32 v[32:33], v[32:33], v[36:37] op_sel_hi:[1,0]
	v_pk_mul_f32 v[30:31], v[30:31], v[36:37] op_sel_hi:[1,0]
	v_pk_mul_f32 v[28:29], v[28:29], v[36:37] op_sel_hi:[1,0]
	v_pk_mul_f32 v[26:27], v[26:27], v[36:37] op_sel_hi:[1,0]
	v_pk_mul_f32 v[24:25], v[24:25], v[36:37] op_sel_hi:[1,0]
	v_pk_mul_f32 v[22:23], v[22:23], v[36:37] op_sel_hi:[1,0]
	v_pk_mul_f32 v[20:21], v[20:21], v[36:37] op_sel_hi:[1,0]
	v_pk_mul_f32 v[18:19], v[18:19], v[36:37] op_sel_hi:[1,0]
	v_mov_b32_e32 v35, v34
	v_mov_b32_e32 v36, v34
	v_mov_b32_e32 v37, v34
	v_mov_b32_e32 v38, v34
	v_mov_b32_e32 v39, v34
	v_mov_b32_e32 v40, v34
	v_mov_b32_e32 v41, v34
	v_mov_b32_e32 v42, v34
	v_mov_b32_e32 v43, v34
	v_mov_b32_e32 v44, v34
	v_mov_b32_e32 v45, v34
	v_mov_b32_e32 v46, v34
	v_mov_b32_e32 v47, v34
	v_mov_b32_e32 v48, v34
	v_mov_b32_e32 v49, v34
	v_mov_b32_e32 v214, v82

.LBB0_530:
	s_andn2_b64 vcc, exec, s[24:25]
	s_cbranch_vccnz .LBB0_532
	s_waitcnt vmcnt(0)
.LBB0_532:
	s_waitcnt lgkmcnt(0)
	s_barrier
.LBB0_534:
	s_add_i32 s0, s75, 0
	v_add3_u32 v138, s0, v0, v229
	v_add_u32_e32 v50, s0, v218
	v_add3_u32 v139, v50, v219, v227
	ds_read_b128 v[50:53], v138
	ds_read_b128 v[54:57], v138 offset:512
	ds_read_b128 v[58:61], v138 offset:4096
	ds_read_b128 v[62:65], v138 offset:4608
	ds_read_b128 v[82:85], v138 offset:8192
	ds_read_b128 v[86:89], v138 offset:8704
	ds_read_b128 v[130:133], v138 offset:12288
	ds_read_b128 v[90:93], v138 offset:12800
	ds_read_b128 v[134:137], v138 offset:16384
	ds_read_b128 v[94:97], v138 offset:16896
	ds_read_b128 v[232:235], v138 offset:20480
	ds_read_b128 v[98:101], v138 offset:20992
	s_waitcnt lgkmcnt(0)
	v_mfma_f32_32x32x16_bf16 v[66:81], v[54:57], v[106:109], v[34:49]
	v_mfma_f32_32x32x16_bf16 v[66:81], v[62:65], v[110:113], v[66:81]
	v_mfma_f32_32x32x16_bf16 v[66:81], v[86:89], v[114:117], v[66:81]
	v_mfma_f32_32x32x16_bf16 v[66:81], v[90:93], v[118:121], v[66:81]
	v_mfma_f32_32x32x16_bf16 v[66:81], v[94:97], v[122:125], v[66:81]
	v_mfma_f32_32x32x16_bf16 v[66:81], v[98:101], v[126:129], v[66:81]
	v_mfma_f32_32x32x16_bf16 v[90:105], v[50:53], v[106:109], v[34:49]
	v_add_u32_e32 v214, v139, v228
	ds_read_b128 v[182:185], v138 offset:1024
	ds_read_b128 v[166:169], v138 offset:1536
	ds_read_b128 v[178:181], v138 offset:5120
	ds_read_b128 v[162:165], v138 offset:5632
	ds_read_b128 v[174:177], v138 offset:9216
	ds_read_b128 v[158:161], v138 offset:9728
	v_mfma_f32_32x32x16_bf16 v[90:105], v[58:61], v[110:113], v[90:105]
	v_mfma_f32_32x32x16_bf16 v[90:105], v[82:85], v[114:117], v[90:105]
	ds_read_b128 v[170:173], v138 offset:13312
	ds_read_b128 v[154:157], v138 offset:13824
	ds_read_b128 v[86:89], v138 offset:17408
	ds_read_b128 v[150:153], v138 offset:17920
	ds_read_b128 v[82:85], v138 offset:21504
	ds_read_b128 v[146:149], v138 offset:22016
	v_mfma_f32_32x32x16_bf16 v[90:105], v[130:133], v[118:121], v[90:105]
	v_mfma_f32_32x32x16_bf16 v[90:105], v[134:137], v[122:125], v[90:105]
	ds_read_b64_tr_b16 v[142:143], v214 offset:24576
	ds_read_b64_tr_b16 v[144:145], v214 offset:25088
	ds_read_b64_tr_b16 v[138:139], v214 offset:25600
	ds_read_b64_tr_b16 v[140:141], v214 offset:26112
	ds_read_b64_tr_b16 v[134:135], v214 offset:26624
	ds_read_b64_tr_b16 v[136:137], v214 offset:27136
	ds_read_b64_tr_b16 v[130:131], v214 offset:27648
	ds_read_b64_tr_b16 v[132:133], v214 offset:28160
	v_mfma_f32_32x32x16_bf16 v[90:105], v[232:235], v[126:129], v[90:105]
	v_max_f32_e32 v50, v66, v66
	s_nop 10
	v_max_f32_e32 v51, v90, v90
	v_max_f32_e32 v50, v51, v50
	v_max3_f32 v50, v50, v91, v67
	v_max3_f32 v50, v50, v92, v68
	v_max3_f32 v50, v50, v93, v69
	v_max3_f32 v50, v50, v94, v70
	v_max3_f32 v50, v50, v95, v71
	v_max3_f32 v50, v50, v96, v72
	v_max3_f32 v50, v50, v97, v73
	v_max3_f32 v50, v50, v98, v74
	v_max3_f32 v50, v50, v99, v75
	v_max3_f32 v50, v50, v100, v76
	v_max3_f32 v50, v50, v101, v77
	v_max3_f32 v50, v50, v102, v78
	v_max3_f32 v50, v50, v103, v79
	v_max3_f32 v50, v50, v104, v80
	v_max3_f32 v50, v50, v105, v81
	v_mov_b32_e32 v51, v50
	s_nop 1
	v_permlane32_swap_b32_e32 v50, v51
	v_max_f32_e32 v51, v51, v51
	v_max_f32_e32 v50, v50, v50
	v_max_f32_e32 v50, v50, v51
	v_cmp_lt_f32_e32 vcc, s69, v50
	s_cbranch_vccz .LBB0_536
	v_max_f32_e32 v34, v50, v50
	v_max_f32_e32 v36, 0, v34
	v_exp_f32_e64 v38, -v36
	v_add_f32_e32 v215, v215, v36
	v_xor_b32_e32 v34, 0x80000000, v215
	v_pk_add_f32 v[90:91], v[90:91], v[36:37] op_sel_hi:[1,0] neg_lo:[0,1] neg_hi:[0,1]
	v_pk_add_f32 v[66:67], v[66:67], v[36:37] op_sel_hi:[1,0] neg_lo:[0,1] neg_hi:[0,1]
	v_pk_add_f32 v[92:93], v[92:93], v[36:37] op_sel_hi:[1,0] neg_lo:[0,1] neg_hi:[0,1]
	v_pk_add_f32 v[68:69], v[68:69], v[36:37] op_sel_hi:[1,0] neg_lo:[0,1] neg_hi:[0,1]
	v_pk_add_f32 v[94:95], v[94:95], v[36:37] op_sel_hi:[1,0] neg_lo:[0,1] neg_hi:[0,1]
	v_pk_add_f32 v[70:71], v[70:71], v[36:37] op_sel_hi:[1,0] neg_lo:[0,1] neg_hi:[0,1]
	v_pk_add_f32 v[96:97], v[96:97], v[36:37] op_sel_hi:[1,0] neg_lo:[0,1] neg_hi:[0,1]
	v_pk_add_f32 v[72:73], v[72:73], v[36:37] op_sel_hi:[1,0] neg_lo:[0,1] neg_hi:[0,1]
	v_pk_add_f32 v[98:99], v[98:99], v[36:37] op_sel_hi:[1,0] neg_lo:[0,1] neg_hi:[0,1]
	v_pk_add_f32 v[74:75], v[74:75], v[36:37] op_sel_hi:[1,0] neg_lo:[0,1] neg_hi:[0,1]
	v_pk_add_f32 v[100:101], v[100:101], v[36:37] op_sel_hi:[1,0] neg_lo:[0,1] neg_hi:[0,1]
	v_pk_add_f32 v[76:77], v[76:77], v[36:37] op_sel_hi:[1,0] neg_lo:[0,1] neg_hi:[0,1]
	v_pk_add_f32 v[102:103], v[102:103], v[36:37] op_sel_hi:[1,0] neg_lo:[0,1] neg_hi:[0,1]
	v_pk_add_f32 v[78:79], v[78:79], v[36:37] op_sel_hi:[1,0] neg_lo:[0,1] neg_hi:[0,1]
	v_pk_mul_f32 v[16:17], v[16:17], v[38:39] op_sel_hi:[1,0]
	v_pk_mul_f32 v[14:15], v[14:15], v[38:39] op_sel_hi:[1,0]
	v_pk_mul_f32 v[12:13], v[12:13], v[38:39] op_sel_hi:[1,0]
	v_pk_mul_f32 v[10:11], v[10:11], v[38:39] op_sel_hi:[1,0]
	v_pk_mul_f32 v[8:9], v[8:9], v[38:39] op_sel_hi:[1,0]
	v_pk_mul_f32 v[6:7], v[6:7], v[38:39] op_sel_hi:[1,0]
	v_pk_mul_f32 v[4:5], v[4:5], v[38:39] op_sel_hi:[1,0]
	v_pk_mul_f32 v[2:3], v[2:3], v[38:39] op_sel_hi:[1,0]
	v_pk_mul_f32 v[32:33], v[32:33], v[38:39] op_sel_hi:[1,0]
	v_pk_mul_f32 v[30:31], v[30:31], v[38:39] op_sel_hi:[1,0]
	v_pk_mul_f32 v[28:29], v[28:29], v[38:39] op_sel_hi:[1,0]
	v_pk_mul_f32 v[26:27], v[26:27], v[38:39] op_sel_hi:[1,0]
	v_pk_mul_f32 v[24:25], v[24:25], v[38:39] op_sel_hi:[1,0]
	v_pk_mul_f32 v[22:23], v[22:23], v[38:39] op_sel_hi:[1,0]
	v_pk_mul_f32 v[20:21], v[20:21], v[38:39] op_sel_hi:[1,0]
	v_pk_mul_f32 v[18:19], v[18:19], v[38:39] op_sel_hi:[1,0]
	v_pk_add_f32 v[104:105], v[104:105], v[36:37] op_sel_hi:[1,0] neg_lo:[0,1] neg_hi:[0,1]
	v_pk_add_f32 v[80:81], v[80:81], v[36:37] op_sel_hi:[1,0] neg_lo:[0,1] neg_hi:[0,1]
	v_mul_f32_e32 v231, v231, v38
	v_mov_b32_e32 v35, v34
	v_mov_b32_e32 v36, v34
	v_mov_b32_e32 v37, v34
	v_mov_b32_e32 v38, v34
	v_mov_b32_e32 v39, v34
	v_mov_b32_e32 v40, v34
	v_mov_b32_e32 v41, v34
	v_mov_b32_e32 v42, v34
	v_mov_b32_e32 v43, v34
	v_mov_b32_e32 v44, v34
	v_mov_b32_e32 v45, v34
	v_mov_b32_e32 v46, v34
	v_mov_b32_e32 v47, v34
	v_mov_b32_e32 v48, v34
	v_mov_b32_e32 v49, v34
.LBB0_536:
	s_waitcnt lgkmcnt(0)
	s_nop 0
	v_mfma_f32_32x32x16_bf16 v[50:65], v[182:185], v[106:109], v[34:49]
	v_exp_f32_e32 v183, v90
	v_exp_f32_e32 v182, v66
	v_exp_f32_e32 v91, v91
	v_pk_add_f32 v[184:185], v[182:183], 0 op_sel_hi:[1,0]
	v_cvt_pk_bf16_f32 v66, v183, v91
	v_mfma_f32_32x32x16_bf16 v[50:65], v[178:181], v[110:113], v[50:65]
	v_exp_f32_e32 v90, v67
	v_exp_f32_e32 v181, v92
	v_exp_f32_e32 v180, v68
	v_pk_add_f32 v[184:185], v[90:91], v[184:185]
	v_cvt_pk_bf16_f32 v178, v182, v90
	v_pk_add_f32 v[90:91], v[180:181], v[184:185]
	v_mfma_f32_32x32x16_bf16 v[50:65], v[174:177], v[114:117], v[50:65]
	v_exp_f32_e32 v93, v93
	v_exp_f32_e32 v92, v69
	v_exp_f32_e32 v175, v94
	v_cvt_pk_bf16_f32 v67, v181, v93
	v_pk_add_f32 v[68:69], v[92:93], v[90:91]
	v_cvt_pk_bf16_f32 v179, v180, v92
	v_mfma_f32_32x32x16_bf16 v[50:65], v[170:173], v[118:121], v[50:65]
	v_exp_f32_e32 v174, v70
	v_exp_f32_e32 v91, v95
	v_exp_f32_e32 v90, v71
	v_pk_add_f32 v[70:71], v[174:175], v[68:69]
	v_cvt_pk_bf16_f32 v68, v175, v91
	v_cvt_pk_bf16_f32 v180, v174, v90
	v_pk_add_f32 v[70:71], v[90:91], v[70:71]
	v_mfma_f32_32x32x16_bf16 v[50:65], v[86:89], v[122:125], v[50:65]
	v_exp_f32_e32 v87, v96
	v_exp_f32_e32 v86, v72
	v_exp_f32_e32 v89, v97
	v_pk_add_f32 v[70:71], v[86:87], v[70:71]
	v_cvt_pk_bf16_f32 v69, v87, v89
	v_mfma_f32_32x32x16_bf16 v[50:65], v[82:85], v[126:129], v[50:65]
	v_exp_f32_e32 v88, v73
	v_exp_f32_e32 v73, v98
	v_exp_f32_e32 v72, v74
	v_pk_add_f32 v[70:71], v[88:89], v[70:71]
	v_cvt_pk_bf16_f32 v181, v86, v88
	v_pk_add_f32 v[70:71], v[72:73], v[70:71]
	v_mfma_f32_32x32x16_bf16 v[82:97], v[166:169], v[106:109], v[34:49]
	v_exp_f32_e32 v99, v99
	v_exp_f32_e32 v98, v75
	v_exp_f32_e32 v167, v100
	v_pk_add_f32 v[168:169], v[98:99], v[70:71]
	v_cvt_pk_bf16_f32 v70, v73, v99
	v_cvt_pk_bf16_f32 v74, v72, v98
	v_mfma_f32_32x32x16_bf16 v[82:97], v[162:165], v[110:113], v[82:97]
	v_exp_f32_e32 v166, v76
	v_exp_f32_e32 v73, v101
	v_exp_f32_e32 v72, v77
	v_pk_add_f32 v[76:77], v[166:167], v[168:169]
	v_cvt_pk_bf16_f32 v71, v167, v73
	v_pk_add_f32 v[76:77], v[72:73], v[76:77]
	v_cvt_pk_bf16_f32 v75, v166, v72
	v_mfma_f32_32x32x16_bf16 v[82:97], v[158:161], v[114:117], v[82:97]
	v_exp_f32_e32 v99, v102
	v_exp_f32_e32 v98, v78
	v_exp_f32_e32 v101, v103
	v_pk_add_f32 v[76:77], v[98:99], v[76:77]
	v_cvt_pk_bf16_f32 v72, v99, v101
	v_mfma_f32_32x32x16_bf16 v[82:97], v[154:157], v[118:121], v[82:97]
	v_exp_f32_e32 v100, v79
	v_exp_f32_e32 v79, v104
	v_exp_f32_e32 v78, v80
	v_pk_add_f32 v[76:77], v[100:101], v[76:77]
	s_nop 0
	v_pk_add_f32 v[102:103], v[78:79], v[76:77]
	v_cvt_pk_bf16_f32 v76, v98, v100
	v_mfma_f32_32x32x16_bf16 v[82:97], v[150:153], v[122:125], v[82:97]
	v_exp_f32_e32 v99, v105
	v_exp_f32_e32 v98, v81
	v_cvt_pk_bf16_f32 v73, v79, v99
	v_pk_add_f32 v[80:81], v[98:99], v[102:103]
	v_cvt_pk_bf16_f32 v77, v78, v98
	v_add_f32_e32 v150, v80, v81
	v_mfma_f32_32x32x16_bf16 v[82:97], v[146:149], v[126:129], v[82:97]
	s_waitcnt vmcnt(0)
	s_barrier
	s_cmp_gt_u32 s13, 13
	s_cselect_b64 s[24:25], -1, 0
	s_and_b64 s[40:41], s[24:25], s[18:19]
	s_and_b64 vcc, exec, s[40:41]
	s_cbranch_vccnz .Lmla_nodma
	s_and_b64 s[24:25], s[24:25], exec
	s_movk_i32 s30, 0xf900
	s_cselect_b32 s25, s15, s9
	s_cselect_b32 s24, s14, s8
	s_cselect_b32 s0, s17, s11
	s_cselect_b32 s4, s16, s10
	s_cselect_b32 s30, s30, 0x100
	s_cmp_gt_i32 s75, 0x9fff
	s_cselect_b32 s31, s68, 0x14000
	s_add_i32 s31, s31, s75
	s_add_u32 s40, s51, s4
	s_addc_u32 s41, s71, s0
	s_add_u32 s54, s44, s24
	s_addc_u32 s55, s45, s25
	s_add_i32 s4, s30, s38
	v_lshl_add_u64 v[154:155], v[190:191], 0, s[4:5]
	s_add_i32 s0, s28, s31
	v_lshl_add_u64 v[152:153], v[216:217], 0, s[24:25]
	v_lshl_add_u64 v[154:155], v[154:155], 4, s[54:55]
	s_add_i32 s24, s4, s12
	s_mov_b32 m0, s0
	v_lshl_add_u64 v[156:157], v[186:187], 0, s[4:5]
	s_ashr_i32 s25, s24, 31
	global_load_lds_dwordx4 v[154:155], off
	v_lshl_add_u64 v[154:155], v[154:155], 0, s[26:27]
	s_add_i32 m0, s0, 0x400
	s_add_i32 s0, s29, s31
	v_lshl_add_u64 v[156:157], v[156:157], 4, s[40:41]
	s_lshl_b64 s[24:25], s[24:25], 6
	global_load_lds_dwordx4 v[154:155], off
	s_add_i32 m0, s0, 0x4000
	s_add_i32 s0, s37, s31
	v_lshl_add_u64 v[152:153], v[152:153], 0, s[24:25]
	global_load_lds_dwordx4 v[156:157], off
	s_add_i32 m0, s0, 0x6000
	s_nop 0
	global_load_lds_dwordx4 v[152:153], off
	v_lshl_add_u64 v[152:153], v[152:153], 0, s[48:49]
	s_add_i32 m0, s0, 0x8000
	s_nop 0
	global_load_lds_dwordx4 v[152:153], off
.Lmla_nodma:
	ds_read_b64_tr_b16 v[78:79], v214 offset:32768
	ds_read_b64_tr_b16 v[80:81], v214 offset:33280
	ds_read_b64_tr_b16 v[98:99], v214 offset:33792
	ds_read_b64_tr_b16 v[100:101], v214 offset:34304
	ds_read_b64_tr_b16 v[102:103], v214 offset:34816
	ds_read_b64_tr_b16 v[104:105], v214 offset:35328
	ds_read_b64_tr_b16 v[146:147], v214 offset:35840
	ds_read_b64_tr_b16 v[148:149], v214 offset:36352
	v_mfma_f32_32x32x16_bf16 v[2:17], v[142:145], v[66:69], v[2:17]
	s_nop 2
	v_max_f32_e32 v142, v82, v82
	v_max_f32_e32 v143, v50, v50
	v_max_f32_e32 v142, v143, v142
	v_mfma_f32_32x32x16_bf16 v[2:17], v[138:141], v[70:73], v[2:17]
	v_max3_f32 v138, v142, v51, v83
	v_max3_f32 v138, v138, v52, v84
	v_max3_f32 v138, v138, v53, v85
	v_mfma_f32_32x32x16_bf16 v[2:17], v[134:137], v[178:181], v[2:17]
	v_max3_f32 v134, v138, v54, v86
	v_max3_f32 v134, v134, v55, v87
	v_max3_f32 v134, v134, v56, v88
	v_mfma_f32_32x32x16_bf16 v[2:17], v[130:133], v[74:77], v[2:17]
	v_max3_f32 v130, v134, v57, v89
	v_max3_f32 v130, v130, v58, v90
	v_max3_f32 v130, v130, v59, v91
	s_waitcnt lgkmcnt(0)
	v_mfma_f32_32x32x16_bf16 v[18:33], v[78:81], v[66:69], v[18:33]
	v_max3_f32 v66, v130, v60, v92
	v_max3_f32 v66, v66, v61, v93
	v_max3_f32 v66, v66, v62, v94
	v_mfma_f32_32x32x16_bf16 v[18:33], v[98:101], v[70:73], v[18:33]
	v_max3_f32 v66, v66, v63, v95
	v_max3_f32 v66, v66, v64, v96
	v_max3_f32 v67, v66, v65, v97
	v_add_f32_e32 v66, v231, v150
	v_mfma_f32_32x32x16_bf16 v[18:33], v[102:105], v[178:181], v[18:33]
	v_mov_b32_e32 v68, v67
	s_nop 1
	v_permlane32_swap_b32_e32 v67, v68
	v_max_f32_e32 v68, v68, v68
	v_max_f32_e32 v67, v67, v67
	v_max_f32_e32 v67, v67, v68
	v_mfma_f32_32x32x16_bf16 v[18:33], v[146:149], v[74:77], v[18:33]
	v_cmp_lt_f32_e32 vcc, s69, v67
	s_cbranch_vccz .LBB0_527
	v_max_f32_e32 v34, v67, v67
	v_max_f32_e32 v36, 0, v34
	v_exp_f32_e64 v38, -v36
	v_add_f32_e32 v215, v215, v36
	v_xor_b32_e32 v34, 0x80000000, v215
	v_pk_add_f32 v[50:51], v[50:51], v[36:37] op_sel_hi:[1,0] neg_lo:[0,1] neg_hi:[0,1]
	v_pk_add_f32 v[82:83], v[82:83], v[36:37] op_sel_hi:[1,0] neg_lo:[0,1] neg_hi:[0,1]
	v_pk_add_f32 v[52:53], v[52:53], v[36:37] op_sel_hi:[1,0] neg_lo:[0,1] neg_hi:[0,1]
	v_pk_add_f32 v[84:85], v[84:85], v[36:37] op_sel_hi:[1,0] neg_lo:[0,1] neg_hi:[0,1]
	v_pk_add_f32 v[54:55], v[54:55], v[36:37] op_sel_hi:[1,0] neg_lo:[0,1] neg_hi:[0,1]
	v_pk_add_f32 v[86:87], v[86:87], v[36:37] op_sel_hi:[1,0] neg_lo:[0,1] neg_hi:[0,1]
	v_pk_add_f32 v[56:57], v[56:57], v[36:37] op_sel_hi:[1,0] neg_lo:[0,1] neg_hi:[0,1]
	v_pk_add_f32 v[88:89], v[88:89], v[36:37] op_sel_hi:[1,0] neg_lo:[0,1] neg_hi:[0,1]
	v_pk_add_f32 v[58:59], v[58:59], v[36:37] op_sel_hi:[1,0] neg_lo:[0,1] neg_hi:[0,1]
	v_pk_add_f32 v[90:91], v[90:91], v[36:37] op_sel_hi:[1,0] neg_lo:[0,1] neg_hi:[0,1]
	v_pk_add_f32 v[60:61], v[60:61], v[36:37] op_sel_hi:[1,0] neg_lo:[0,1] neg_hi:[0,1]
	v_pk_add_f32 v[92:93], v[92:93], v[36:37] op_sel_hi:[1,0] neg_lo:[0,1] neg_hi:[0,1]
	v_pk_add_f32 v[62:63], v[62:63], v[36:37] op_sel_hi:[1,0] neg_lo:[0,1] neg_hi:[0,1]
	v_pk_add_f32 v[94:95], v[94:95], v[36:37] op_sel_hi:[1,0] neg_lo:[0,1] neg_hi:[0,1]
	v_pk_mul_f32 v[16:17], v[16:17], v[38:39] op_sel_hi:[1,0]
	v_pk_mul_f32 v[14:15], v[14:15], v[38:39] op_sel_hi:[1,0]
	v_pk_mul_f32 v[12:13], v[12:13], v[38:39] op_sel_hi:[1,0]
	v_pk_mul_f32 v[10:11], v[10:11], v[38:39] op_sel_hi:[1,0]
	v_pk_mul_f32 v[8:9], v[8:9], v[38:39] op_sel_hi:[1,0]
	v_pk_mul_f32 v[6:7], v[6:7], v[38:39] op_sel_hi:[1,0]
	v_pk_mul_f32 v[4:5], v[4:5], v[38:39] op_sel_hi:[1,0]
	v_pk_mul_f32 v[2:3], v[2:3], v[38:39] op_sel_hi:[1,0]
	v_pk_mul_f32 v[32:33], v[32:33], v[38:39] op_sel_hi:[1,0]
	v_pk_mul_f32 v[30:31], v[30:31], v[38:39] op_sel_hi:[1,0]
	v_pk_mul_f32 v[28:29], v[28:29], v[38:39] op_sel_hi:[1,0]
	v_pk_mul_f32 v[26:27], v[26:27], v[38:39] op_sel_hi:[1,0]
	v_pk_mul_f32 v[24:25], v[24:25], v[38:39] op_sel_hi:[1,0]
	v_pk_mul_f32 v[22:23], v[22:23], v[38:39] op_sel_hi:[1,0]
	v_pk_mul_f32 v[20:21], v[20:21], v[38:39] op_sel_hi:[1,0]
	v_pk_mul_f32 v[18:19], v[18:19], v[38:39] op_sel_hi:[1,0]
	v_pk_add_f32 v[64:65], v[64:65], v[36:37] op_sel_hi:[1,0] neg_lo:[0,1] neg_hi:[0,1]
	v_pk_add_f32 v[96:97], v[96:97], v[36:37] op_sel_hi:[1,0] neg_lo:[0,1] neg_hi:[0,1]
	v_mul_f32_e32 v66, v66, v38
	v_mov_b32_e32 v35, v34
	v_mov_b32_e32 v36, v34
	v_mov_b32_e32 v37, v34
	v_mov_b32_e32 v38, v34
	v_mov_b32_e32 v39, v34
	v_mov_b32_e32 v40, v34
	v_mov_b32_e32 v41, v34
	v_mov_b32_e32 v42, v34
	v_mov_b32_e32 v43, v34
	v_mov_b32_e32 v44, v34
	v_mov_b32_e32 v45, v34
	v_mov_b32_e32 v46, v34
	v_mov_b32_e32 v47, v34
	v_mov_b32_e32 v48, v34
	v_mov_b32_e32 v49, v34
	s_branch .LBB0_527
.Lmla_exit:
	s_cmp_lg_u32 s101, 0
	s_cbranch_scc1 .LBB0_538
	s_barrier

	.amdhsa_kernel _Z6mk_fwd6Params
		.amdhsa_group_segment_fixed_size 0
		.amdhsa_private_segment_fixed_size 0
		.amdhsa_kernarg_size 400
		.amdhsa_user_sgpr_count 2
		.amdhsa_user_sgpr_dispatch_ptr 0
		.amdhsa_user_sgpr_queue_ptr 0
		.amdhsa_user_sgpr_kernarg_segment_ptr 1
		.amdhsa_user_sgpr_dispatch_id 0
		.amdhsa_user_sgpr_kernarg_preload_length 0
		.amdhsa_user_sgpr_kernarg_preload_offset 0
		.amdhsa_user_sgpr_private_segment_size 0
		.amdhsa_uses_dynamic_stack 0
		.amdhsa_enable_private_segment 0
		.amdhsa_system_sgpr_workgroup_id_x 1
		.amdhsa_system_sgpr_workgroup_id_y 0
		.amdhsa_system_sgpr_workgroup_id_z 0
		.amdhsa_system_sgpr_workgroup_info 0
		.amdhsa_system_vgpr_workitem_id 2
		.amdhsa_next_free_vgpr 252
		.amdhsa_next_free_sgpr 102
		.amdhsa_accum_offset 252
		.amdhsa_reserve_vcc 1
		.amdhsa_float_round_mode_32 0
		.amdhsa_float_round_mode_16_64 0
		.amdhsa_float_denorm_mode_32 3
		.amdhsa_float_denorm_mode_16_64 3
		.amdhsa_dx10_clamp 1
		.amdhsa_ieee_mode 1
		.amdhsa_fp16_overflow 0
		.amdhsa_tg_split 0
		.amdhsa_exception_fp_ieee_invalid_op 0
		.amdhsa_exception_fp_denorm_src 0
		.amdhsa_exception_fp_ieee_div_zero 0
		.amdhsa_exception_fp_ieee_overflow 0
		.amdhsa_exception_fp_ieee_underflow 0
		.amdhsa_exception_fp_ieee_inexact 0
		.amdhsa_exception_int_div_zero 0
	.end_amdhsa_kernel

amdhsa.kernels:
  - .agpr_count:     0
    .args:
      - .offset:         0
        .size:           144
        .value_kind:     by_value
      - .offset:         144
        .size:           4
        .value_kind:     hidden_block_count_x
      - .offset:         148
        .size:           4
        .value_kind:     hidden_block_count_y
      - .offset:         152
        .size:           4
        .value_kind:     hidden_block_count_z
      - .offset:         156
        .size:           2
        .value_kind:     hidden_group_size_x
      - .offset:         158
        .size:           2
        .value_kind:     hidden_group_size_y
      - .offset:         160
        .size:           2
        .value_kind:     hidden_group_size_z
      - .offset:         162
        .size:           2
        .value_kind:     hidden_remainder_x
      - .offset:         164
        .size:           2
        .value_kind:     hidden_remainder_y
      - .offset:         166
        .size:           2
        .value_kind:     hidden_remainder_z
      - .offset:         184
        .size:           8
        .value_kind:     hidden_global_offset_x
      - .offset:         192
        .size:           8
        .value_kind:     hidden_global_offset_y
      - .offset:         200
        .size:           8
        .value_kind:     hidden_global_offset_z
      - .offset:         208
        .size:           2
        .value_kind:     hidden_grid_dims
      - .offset:         232
        .size:           8
        .value_kind:     hidden_multigrid_sync_arg
      - .offset:         264
        .size:           4
        .value_kind:     hidden_dynamic_lds_size
    .group_segment_fixed_size: 0
    .kernarg_segment_align: 8
    .kernarg_segment_size: 400
    .language:       OpenCL C
    .language_version:
      - 2
      - 0
    .max_flat_workgroup_size: 512
    .name:           _Z6mk_fwd6Params
    .private_segment_fixed_size: 0
    .sgpr_count:     108
    .sgpr_spill_count: 237
    .symbol:         _Z6mk_fwd6Params.kd
    .uniform_work_group_size: 1
    .uses_dynamic_stack: false
    .vgpr_count:     252
    .vgpr_spill_count: 0
    .wavefront_size: 64
